# P7 third-round tail tiles shared by 4 workgroups of the same XCD, each issuing only its quadrant's MFMA blocks and stores
# speedup vs baseline: 1.0035x; 1.0015x over previous
;     __host__ __device__ bool next(int i, Unit& u) const {
;         i += ibeg; if (i >= iend) return false;
;         const long L = (long)i * G + c; if (L >= nwg) return false;
;         int wgid = (int)L; { const int q = nwg / NXCD, r = nwg % NXCD, xcd = wgid % NXCD, off = wgid / NXCD; wgid = (xcd < r ? xcd * (q + 1) : r * (q + 1) + (xcd - r) * q) + off; }
;         const int nig = WGM * nN, gid = wgid / nig, fm = gid * WGM, gsz = (nM - fm) < WGM ? (nM - fm) : WGM;
;         u.pm = fm + ((wgid % nig) % gsz); u.pn = (wgid % nig) / gsz; u.mask = 15; return true;
; template <class Epi, class Sched, bool ALIGN_EPI = false, bool SP2 = false>
; __device__ __forceinline__ void gemm_phase(PG8_LAS unsigned char* lds, const Gemm g, const Sched& S, const Epi& E, int tid_in) {
;     ...
;         const bool has_next = S.next(ui + 1, nxt);
;         const char* nA = has_next ? (const char*)g.A + (size_t)nxt.pm * tstep : cA; const char* nB = has_next ? (const char*)g.Bt + (size_t)nxt.pn * tstep : cB;
.LBB0_1547:
	s_mov_b32 s68, 15
	s_cmp_eq_u32 s46, 2
	s_cbranch_scc0 .Lp7s_full
	s_lshr_b32 s69, s72, 3
	s_lshl_b32 s68, 1, s69
.Lp7s_full:
	s_mov_b32 s19, s46
	s_add_i32 s46, s46, 1
	s_cmp_gt_u32 s19, 0x3ffffffe
	s_mov_b64 s[22:23], 0
	s_cbranch_scc1 .LBB0_1550
	v_readlane_b32 s22, v253, 38
	v_readlane_b32 s23, v253, 39
	s_mul_i32 s19, s46, s23
	s_mul_hi_u32 s21, s46, s22
	s_add_i32 s21, s21, s19
	s_mul_i32 s19, s46, s22
	s_add_u32 s24, s19, s72
	s_addc_u32 s25, s21, s41
	s_cmp_eq_u32 s46, 2
	s_cbranch_scc0 .Lp7s_tok
	s_cmp_lt_u32 s72, 32
	s_cbranch_scc0 .Lp7s_tok
	s_and_b32 s24, s72, 7
	s_or_b32 s24, s24, 0x200
	s_mov_b32 s25, 0
.Lp7s_tok:
	v_cmp_gt_i64_e32 vcc, s[24:25], v[140:141]
	s_mov_b64 s[22:23], 0
	s_cbranch_vccnz .LBB0_1550
	s_ashr_i32 s18, s24, 31
	s_lshr_b32 s18, s18, 29
	s_add_i32 s18, s24, s18
	s_ashr_i32 s19, s18, 3
	s_and_b32 s18, s18, -8
	s_sub_i32 s18, s24, s18
	s_cmp_lt_i32 s18, 0
	s_cselect_b32 s20, s42, 0x41
	s_mul_i32 s18, s18, s20
	s_add_i32 s18, s18, s19
	s_ashr_i32 s19, s18, 31
	s_lshr_b32 s19, s19, 26
	s_add_i32 s19, s18, s19
	s_ashr_i32 s20, s19, 6
	s_lshl_b32 s20, s20, 3
	s_sub_i32 s21, 0x41, s20
	s_min_i32 s21, s21, 8
	s_abs_i32 s22, s21
	v_cvt_f32_u32_e32 v0, s22
	s_sub_i32 s24, 0, s22
	s_andn2_b32 s19, s19, 63
	s_sub_i32 s19, s18, s19
	v_rcp_iflag_f32_e32 v0, v0
	s_abs_i32 s18, s19
	s_xor_b32 s23, s19, s21
	s_ashr_i32 s23, s23, 31
	v_mul_f32_e32 v0, 0x4f7ffffe, v0
	v_cvt_u32_f32_e32 v0, v0
	s_nop 0
	v_readfirstlane_b32 s25, v0
	s_mul_i32 s24, s24, s25
	s_mul_hi_u32 s24, s25, s24
	s_add_i32 s25, s25, s24
	s_mul_hi_u32 s24, s18, s25
	s_mul_i32 s25, s24, s22
	s_sub_i32 s18, s18, s25
	s_add_i32 s26, s24, 1
	s_sub_i32 s25, s18, s22
	s_cmp_ge_u32 s18, s22
	s_cselect_b32 s24, s26, s24
	s_cselect_b32 s18, s25, s18
	s_add_i32 s25, s24, 1
	s_cmp_ge_u32 s18, s22
	s_cselect_b32 s18, s25, s24
	s_xor_b32 s18, s18, s23
	s_sub_i32 s18, s18, s23
	s_mul_i32 s21, s18, s21
	s_sub_i32 s19, s19, s21
	s_add_i32 s20, s20, s19
	s_mov_b64 s[22:23], -1

; #define PG8_STAGE(bufoff, gbase, voff) do { _Pragma("unroll") for (int _i = 0; _i < 2; ++_i) \
;         __builtin_amdgcn_global_load_lds((const unsigned*)((const char*)(gbase) + (voff)[_i]), (PG8_LAS unsigned*)(lds + (bufoff) + ldsw + _i * 8192), 16, 0, 0); } while (0)
; #define PG8_LDA(dst, b, h) do { _Pragma("unroll") for (int m = 0; m < 4; ++m) _Pragma("unroll") for (int k = 0; k < 2; ++k) dst[m][k] = *(const PG8_LAS bf16x8*)(lds + PG8_SA(b, h) + aoff + m * 2048 + k * 1024); } while (0)
; #define PG8_LDB(dst, b, h) do { _Pragma("unroll") for (int n = 0; n < 2; ++n) _Pragma("unroll") for (int k = 0; k < 2; ++k) dst[n][k] = *(const PG8_LAS bf16x8*)(lds + PG8_SB(b, h) + boff + n * 2048 + k * 1024); } while (0)
; #define PG8_MMA(ai, bj, At, Bt) do { __builtin_amdgcn_s_setprio(1); _Pragma("unroll") for (int m = 0; m < 4; ++m) _Pragma("unroll") for (int n = 0; n < 2; ++n) _Pragma("unroll") for (int k = 0; k < 2; ++k) \
;         acc[ai][bj][m][n] = __builtin_amdgcn_mfma_f32_16x16x32_bf16(Bt[n][k], At[m][k], acc[ai][bj][m][n], 0, 0, 0); __builtin_amdgcn_s_setprio(0); } while (0)
; #define PG8_WAIT_V(n) asm volatile("s_waitcnt vmcnt(" #n ")" ::: "memory")
; #define PG8_WAIT_L(n) asm volatile("s_waitcnt lgkmcnt(" #n ")" ::: "memory")
; #define PG8_BAR __builtin_amdgcn_s_barrier()
; #define PG8_SCHED __builtin_amdgcn_sched_barrier(0)
; template <class Epi, class Sched, bool ALIGN_EPI = false, bool SP2 = false>
; __device__ __forceinline__ void gemm_phase(PG8_LAS unsigned char* lds, const Gemm g, const Sched& S, const Epi& E, int tid_in) {
;     ...
;             PG8_LDB(B0, 0, 0); PG8_LDB(B1, 0, 1); PG8_SCHED; PG8_LDA(At, 0, 0); PG8_STAGE(PG8_SA(1, 1), a1 + hstep, voffA);
;             PG8_WAIT_V(8); PG8_WAIT_L(0); PG8_BAR; PG8_MMA(0, 0, At, B0); PG8_MMA(0, 1, At, B1); PG8_BAR; PG8_SCHED;
.LBB0_1551:
	ds_read_b128 v[150:153], v147
	ds_read_b128 v[154:157], v147 offset:1024
	ds_read_b128 v[158:161], v147 offset:2048
	ds_read_b128 v[162:165], v147 offset:3072
	ds_read_b128 v[166:169], v148
	ds_read_b128 v[170:173], v148 offset:1024
	ds_read_b128 v[174:177], v148 offset:2048
	ds_read_b128 v[178:181], v148 offset:3072
	s_add_u32 s34, s30, 0xfff00080
	s_addc_u32 s35, s31, -1
	s_cmp_eq_u32 s60, 60
	s_cselect_b32 s37, s21, s35
	s_cselect_b32 s36, s56, s34
	s_cselect_b32 s35, s19, s59
	s_cselect_b32 s34, s57, s58
	v_lshl_add_u64 v[142:143], s[30:31], 0, v[136:137]
	s_add_i32 m0, s29, 0xc000
	ds_read_b128 v[182:185], v149
	ds_read_b128 v[186:189], v149 offset:1024
	ds_read_b128 v[190:193], v149 offset:2048
	ds_read_b128 v[194:197], v149 offset:3072
	ds_read_b128 v[198:201], v149 offset:4096
	ds_read_b128 v[202:205], v149 offset:5120
	ds_read_b128 v[206:209], v149 offset:6144
	ds_read_b128 v[210:213], v149 offset:7168
	global_load_lds_dwordx4 v[142:143], off
	v_lshl_add_u64 v[142:143], s[30:31], 0, v[138:139]
	s_add_i32 m0, s29, 0xe000
	s_nop 0
	global_load_lds_dwordx4 v[142:143], off
	s_waitcnt vmcnt(8)
	s_waitcnt lgkmcnt(0)
	s_barrier
	s_setprio 1
	s_waitcnt lgkmcnt(0)
	s_bitcmp1_b32 s68, 0
	s_cbranch_scc0 .Lp7s_m0
	v_mfma_f32_16x16x32_bf16 v[124:127], v[150:153], v[182:185], v[124:127]
	v_mfma_f32_16x16x32_bf16 v[120:123], v[158:161], v[182:185], v[120:123]
	v_mfma_f32_16x16x32_bf16 v[112:115], v[150:153], v[190:193], v[112:115]
	v_mfma_f32_16x16x32_bf16 v[104:107], v[158:161], v[190:193], v[104:107]
	v_mfma_f32_16x16x32_bf16 v[96:99], v[150:153], v[198:201], v[96:99]
	v_mfma_f32_16x16x32_bf16 v[88:91], v[158:161], v[198:201], v[88:91]
	v_mfma_f32_16x16x32_bf16 v[80:83], v[150:153], v[206:209], v[80:83]
	v_mfma_f32_16x16x32_bf16 v[72:75], v[158:161], v[206:209], v[72:75]
	v_mfma_f32_16x16x32_bf16 v[124:127], v[154:157], v[186:189], v[124:127]
	v_mfma_f32_16x16x32_bf16 v[120:123], v[162:165], v[186:189], v[120:123]
	v_mfma_f32_16x16x32_bf16 v[112:115], v[154:157], v[194:197], v[112:115]
	v_mfma_f32_16x16x32_bf16 v[104:107], v[162:165], v[194:197], v[104:107]
	v_mfma_f32_16x16x32_bf16 v[96:99], v[154:157], v[202:205], v[96:99]
	v_mfma_f32_16x16x32_bf16 v[88:91], v[162:165], v[202:205], v[88:91]
	v_mfma_f32_16x16x32_bf16 v[80:83], v[154:157], v[210:213], v[80:83]
	v_mfma_f32_16x16x32_bf16 v[72:75], v[162:165], v[210:213], v[72:75]
.Lp7s_m0:
	s_setprio 0
	s_setprio 1
	s_bitcmp1_b32 s68, 1
	s_cbranch_scc0 .Lp7s_m1
	v_mfma_f32_16x16x32_bf16 v[116:119], v[166:169], v[182:185], v[116:119]
	v_mfma_f32_16x16x32_bf16 v[108:111], v[174:177], v[182:185], v[108:111]
	v_mfma_f32_16x16x32_bf16 v[100:103], v[166:169], v[190:193], v[100:103]
	v_mfma_f32_16x16x32_bf16 v[92:95], v[174:177], v[190:193], v[92:95]
	v_mfma_f32_16x16x32_bf16 v[84:87], v[166:169], v[198:201], v[84:87]
	v_mfma_f32_16x16x32_bf16 v[76:79], v[174:177], v[198:201], v[76:79]
	v_mfma_f32_16x16x32_bf16 v[68:71], v[166:169], v[206:209], v[68:71]
	v_mfma_f32_16x16x32_bf16 v[64:67], v[174:177], v[206:209], v[64:67]
	v_mfma_f32_16x16x32_bf16 v[116:119], v[170:173], v[186:189], v[116:119]
	v_mfma_f32_16x16x32_bf16 v[108:111], v[178:181], v[186:189], v[108:111]
	v_mfma_f32_16x16x32_bf16 v[100:103], v[170:173], v[194:197], v[100:103]
	v_mfma_f32_16x16x32_bf16 v[92:95], v[178:181], v[194:197], v[92:95]
	v_mfma_f32_16x16x32_bf16 v[84:87], v[170:173], v[202:205], v[84:87]
	v_mfma_f32_16x16x32_bf16 v[76:79], v[178:181], v[202:205], v[76:79]
	v_mfma_f32_16x16x32_bf16 v[68:71], v[170:173], v[210:213], v[68:71]
	v_mfma_f32_16x16x32_bf16 v[64:67], v[178:181], v[210:213], v[64:67]
; #define PG8_STAGE(bufoff, gbase, voff) do { _Pragma("unroll") for (int _i = 0; _i < 2; ++_i) \
;         __builtin_amdgcn_global_load_lds((const unsigned*)((const char*)(gbase) + (voff)[_i]), (PG8_LAS unsigned*)(lds + (bufoff) + ldsw + _i * 8192), 16, 0, 0); } while (0)
; #define PG8_LDA(dst, b, h) do { _Pragma("unroll") for (int m = 0; m < 4; ++m) _Pragma("unroll") for (int k = 0; k < 2; ++k) dst[m][k] = *(const PG8_LAS bf16x8*)(lds + PG8_SA(b, h) + aoff + m * 2048 + k * 1024); } while (0)
; #define PG8_LDB(dst, b, h) do { _Pragma("unroll") for (int n = 0; n < 2; ++n) _Pragma("unroll") for (int k = 0; k < 2; ++k) dst[n][k] = *(const PG8_LAS bf16x8*)(lds + PG8_SB(b, h) + boff + n * 2048 + k * 1024); } while (0)
; #define PG8_MMA(ai, bj, At, Bt) do { __builtin_amdgcn_s_setprio(1); _Pragma("unroll") for (int m = 0; m < 4; ++m) _Pragma("unroll") for (int n = 0; n < 2; ++n) _Pragma("unroll") for (int k = 0; k < 2; ++k) \
;         acc[ai][bj][m][n] = __builtin_amdgcn_mfma_f32_16x16x32_bf16(Bt[n][k], At[m][k], acc[ai][bj][m][n], 0, 0, 0); __builtin_amdgcn_s_setprio(0); } while (0)
; #define PG8_WAIT_V(n) asm volatile("s_waitcnt vmcnt(" #n ")" ::: "memory")
; #define PG8_WAIT_L(n) asm volatile("s_waitcnt lgkmcnt(" #n ")" ::: "memory")
; #define PG8_BAR __builtin_amdgcn_s_barrier()
; #define PG8_SCHED __builtin_amdgcn_sched_barrier(0)
; template <class Epi, class Sched, bool ALIGN_EPI = false, bool SP2 = false>
; __device__ __forceinline__ void gemm_phase(PG8_LAS unsigned char* lds, const Gemm g, const Sched& S, const Epi& E, int tid_in) {
;     ...
;             PG8_WAIT_V(8); PG8_WAIT_L(0); PG8_BAR; PG8_MMA(0, 0, At, B0); PG8_MMA(0, 1, At, B1); PG8_BAR; PG8_SCHED;
;             PG8_LDA(At, 0, 1); PG8_STAGE(PG8_SB(0, 0), b2, voffB); PG8_STAGE(PG8_SB(0, 1), b2 + hstep, voffB); PG8_STAGE(PG8_SA(0, 0), a2, voffA);
;             PG8_WAIT_V(8); PG8_WAIT_L(0); PG8_BAR; PG8_MMA(1, 0, At, B0); PG8_MMA(1, 1, At, B1); PG8_BAR; PG8_SCHED;
;             PG8_LDB(B0, 1, 0); PG8_LDB(B1, 1, 1); PG8_SCHED; PG8_LDA(At, 1, 0); PG8_STAGE(PG8_SA(0, 1), a2 + hstep, voffA);
;             PG8_WAIT_V(8); PG8_WAIT_L(0); PG8_BAR; PG8_MMA(0, 0, At, B0); PG8_MMA(0, 1, At, B1); PG8_BAR; PG8_SCHED;
.Lp7s_m1:
	s_setprio 0
	s_barrier
	s_add_i32 s61, s49, s40
	v_lshl_add_u64 v[142:143], s[34:35], 0, v[132:133]
	s_mov_b32 m0, s61
	ds_read_b128 v[182:185], v149 offset:16384
	ds_read_b128 v[186:189], v149 offset:17408
	ds_read_b128 v[190:193], v149 offset:18432
	ds_read_b128 v[194:197], v149 offset:19456
	ds_read_b128 v[198:201], v149 offset:20480
	ds_read_b128 v[202:205], v149 offset:21504
	ds_read_b128 v[206:209], v149 offset:22528
	ds_read_b128 v[210:213], v149 offset:23552
	global_load_lds_dwordx4 v[142:143], off
	s_add_i32 m0, s61, 0x2000
	s_add_u32 s62, s34, 0x100000
	v_lshl_add_u64 v[214:215], s[34:35], 0, v[128:129]
	s_addc_u32 s63, s35, 0
	s_add_i32 s61, s50, s40
	global_load_lds_dwordx4 v[214:215], off
	v_lshl_add_u64 v[216:217], s[62:63], 0, v[132:133]
	s_mov_b32 m0, s61
	v_lshl_add_u64 v[218:219], s[36:37], 0, v[130:131]
	global_load_lds_dwordx4 v[216:217], off
	v_lshl_add_u64 v[216:217], s[62:63], 0, v[128:129]
	s_add_i32 m0, s61, 0x2000
	s_nop 0
	global_load_lds_dwordx4 v[216:217], off
	v_lshl_add_u64 v[216:217], s[36:37], 0, v[134:135]
	s_mov_b32 m0, s29
	s_nop 0
	global_load_lds_dwordx4 v[216:217], off
	s_mov_b32 m0, s43
	s_nop 0
	global_load_lds_dwordx4 v[218:219], off
	s_waitcnt vmcnt(8)
	s_waitcnt lgkmcnt(0)
	s_barrier
	s_setprio 1
	s_waitcnt lgkmcnt(0)
	s_bitcmp1_b32 s68, 2
	s_cbranch_scc0 .Lp7s_m2
	v_mfma_f32_16x16x32_bf16 v[60:63], v[150:153], v[182:185], v[60:63]
	v_mfma_f32_16x16x32_bf16 v[56:59], v[158:161], v[182:185], v[56:59]
	v_mfma_f32_16x16x32_bf16 v[48:51], v[150:153], v[190:193], v[48:51]
	v_mfma_f32_16x16x32_bf16 v[40:43], v[158:161], v[190:193], v[40:43]
	v_mfma_f32_16x16x32_bf16 v[32:35], v[150:153], v[198:201], v[32:35]
	v_mfma_f32_16x16x32_bf16 v[24:27], v[158:161], v[198:201], v[24:27]
	v_mfma_f32_16x16x32_bf16 v[16:19], v[150:153], v[206:209], v[16:19]
	v_mfma_f32_16x16x32_bf16 v[8:11], v[158:161], v[206:209], v[8:11]
	v_mfma_f32_16x16x32_bf16 v[60:63], v[154:157], v[186:189], v[60:63]
	v_mfma_f32_16x16x32_bf16 v[56:59], v[162:165], v[186:189], v[56:59]
	v_mfma_f32_16x16x32_bf16 v[48:51], v[154:157], v[194:197], v[48:51]
	v_mfma_f32_16x16x32_bf16 v[40:43], v[162:165], v[194:197], v[40:43]
	v_mfma_f32_16x16x32_bf16 v[32:35], v[154:157], v[202:205], v[32:35]
	v_mfma_f32_16x16x32_bf16 v[24:27], v[162:165], v[202:205], v[24:27]
	v_mfma_f32_16x16x32_bf16 v[16:19], v[154:157], v[210:213], v[16:19]
	v_mfma_f32_16x16x32_bf16 v[8:11], v[162:165], v[210:213], v[8:11]
.Lp7s_m2:
	s_setprio 0
	s_setprio 1
	s_bitcmp1_b32 s68, 3
	s_cbranch_scc0 .Lp7s_m3
	v_mfma_f32_16x16x32_bf16 v[52:55], v[166:169], v[182:185], v[52:55]
	v_mfma_f32_16x16x32_bf16 v[44:47], v[174:177], v[182:185], v[44:47]
	v_mfma_f32_16x16x32_bf16 v[36:39], v[166:169], v[190:193], v[36:39]
	v_mfma_f32_16x16x32_bf16 v[28:31], v[174:177], v[190:193], v[28:31]
	v_mfma_f32_16x16x32_bf16 v[20:23], v[166:169], v[198:201], v[20:23]
	v_mfma_f32_16x16x32_bf16 v[12:15], v[174:177], v[198:201], v[12:15]
	v_mfma_f32_16x16x32_bf16 v[4:7], v[166:169], v[206:209], v[4:7]
	v_mfma_f32_16x16x32_bf16 v[0:3], v[174:177], v[206:209], v[0:3]
	v_mfma_f32_16x16x32_bf16 v[52:55], v[170:173], v[186:189], v[52:55]
	v_mfma_f32_16x16x32_bf16 v[44:47], v[178:181], v[186:189], v[44:47]
	v_mfma_f32_16x16x32_bf16 v[36:39], v[170:173], v[194:197], v[36:39]
	v_mfma_f32_16x16x32_bf16 v[28:31], v[178:181], v[194:197], v[28:31]
	v_mfma_f32_16x16x32_bf16 v[20:23], v[170:173], v[202:205], v[20:23]
	v_mfma_f32_16x16x32_bf16 v[12:15], v[178:181], v[202:205], v[12:15]
	v_mfma_f32_16x16x32_bf16 v[4:7], v[170:173], v[210:213], v[4:7]
	v_mfma_f32_16x16x32_bf16 v[0:3], v[178:181], v[210:213], v[0:3]
.Lp7s_m3:
	s_setprio 0
	s_barrier
	s_add_i32 s61, 0, 0x18000
	s_add_i32 s62, 0, 0x1c000
	v_add_u32_e32 v162, s61, v145
	v_add_u32_e32 v178, s62, v145
	ds_read_b128 v[150:153], v162
	ds_read_b128 v[154:157], v162 offset:1024
	ds_read_b128 v[158:161], v162 offset:2048
	ds_read_b128 v[162:165], v162 offset:3072
	ds_read_b128 v[166:169], v178
	ds_read_b128 v[170:173], v178 offset:1024
	ds_read_b128 v[174:177], v178 offset:2048
	ds_read_b128 v[178:181], v178 offset:3072
	s_add_u32 s36, s36, 0x100000
	s_addc_u32 s37, s37, 0
	s_mov_b32 m0, s44
	v_lshl_add_u64 v[220:221], s[36:37], 0, v[134:135]
	ds_read_b128 v[182:185], v149 offset:32768
	ds_read_b128 v[186:189], v149 offset:33792
	ds_read_b128 v[190:193], v149 offset:34816
	ds_read_b128 v[194:197], v149 offset:35840
	ds_read_b128 v[198:201], v149 offset:36864
	ds_read_b128 v[202:205], v149 offset:37888
	ds_read_b128 v[206:209], v149 offset:38912
	ds_read_b128 v[210:213], v149 offset:39936
	global_load_lds_dwordx4 v[220:221], off
	v_lshl_add_u64 v[220:221], s[36:37], 0, v[130:131]
	s_mov_b32 m0, s45
	s_nop 0
	global_load_lds_dwordx4 v[220:221], off
	s_waitcnt vmcnt(8)
	s_waitcnt lgkmcnt(0)
	s_barrier
	s_setprio 1
	s_waitcnt lgkmcnt(0)
	s_bitcmp1_b32 s68, 0
	s_cbranch_scc0 .Lp7s_m4
	v_mfma_f32_16x16x32_bf16 v[124:127], v[150:153], v[182:185], v[124:127]
	v_mfma_f32_16x16x32_bf16 v[120:123], v[158:161], v[182:185], v[120:123]
	v_mfma_f32_16x16x32_bf16 v[112:115], v[150:153], v[190:193], v[112:115]
	v_mfma_f32_16x16x32_bf16 v[104:107], v[158:161], v[190:193], v[104:107]
	v_mfma_f32_16x16x32_bf16 v[96:99], v[150:153], v[198:201], v[96:99]
	v_mfma_f32_16x16x32_bf16 v[88:91], v[158:161], v[198:201], v[88:91]
	v_mfma_f32_16x16x32_bf16 v[80:83], v[150:153], v[206:209], v[80:83]
	v_mfma_f32_16x16x32_bf16 v[72:75], v[158:161], v[206:209], v[72:75]
	v_mfma_f32_16x16x32_bf16 v[124:127], v[154:157], v[186:189], v[124:127]
	v_mfma_f32_16x16x32_bf16 v[120:123], v[162:165], v[186:189], v[120:123]
	v_mfma_f32_16x16x32_bf16 v[112:115], v[154:157], v[194:197], v[112:115]
	v_mfma_f32_16x16x32_bf16 v[104:107], v[162:165], v[194:197], v[104:107]
	v_mfma_f32_16x16x32_bf16 v[96:99], v[154:157], v[202:205], v[96:99]
	v_mfma_f32_16x16x32_bf16 v[88:91], v[162:165], v[202:205], v[88:91]
	v_mfma_f32_16x16x32_bf16 v[80:83], v[154:157], v[210:213], v[80:83]
	v_mfma_f32_16x16x32_bf16 v[72:75], v[162:165], v[210:213], v[72:75]

; #define PG8_STAGE(bufoff, gbase, voff) do { _Pragma("unroll") for (int _i = 0; _i < 2; ++_i) \
;         __builtin_amdgcn_global_load_lds((const unsigned*)((const char*)(gbase) + (voff)[_i]), (PG8_LAS unsigned*)(lds + (bufoff) + ldsw + _i * 8192), 16, 0, 0); } while (0)
; #define PG8_LDA(dst, b, h) do { _Pragma("unroll") for (int m = 0; m < 4; ++m) _Pragma("unroll") for (int k = 0; k < 2; ++k) dst[m][k] = *(const PG8_LAS bf16x8*)(lds + PG8_SA(b, h) + aoff + m * 2048 + k * 1024); } while (0)
; #define PG8_MMA(ai, bj, At, Bt) do { __builtin_amdgcn_s_setprio(1); _Pragma("unroll") for (int m = 0; m < 4; ++m) _Pragma("unroll") for (int n = 0; n < 2; ++n) _Pragma("unroll") for (int k = 0; k < 2; ++k) \
;         acc[ai][bj][m][n] = __builtin_amdgcn_mfma_f32_16x16x32_bf16(Bt[n][k], At[m][k], acc[ai][bj][m][n], 0, 0, 0); __builtin_amdgcn_s_setprio(0); } while (0)
; #define PG8_WAIT_V(n) asm volatile("s_waitcnt vmcnt(" #n ")" ::: "memory")
; #define PG8_WAIT_L(n) asm volatile("s_waitcnt lgkmcnt(" #n ")" ::: "memory")
; #define PG8_BAR __builtin_amdgcn_s_barrier()
; #define PG8_SCHED __builtin_amdgcn_sched_barrier(0)
; template <class Epi, class Sched, bool ALIGN_EPI = false, bool SP2 = false>
; __device__ __forceinline__ void gemm_phase(PG8_LAS unsigned char* lds, const Gemm g, const Sched& S, const Epi& E, int tid_in) {
;     ...
;             PG8_LDA(At, 1, 1); PG8_STAGE(PG8_SB(1, 0), b3, voffB); PG8_STAGE(PG8_SB(1, 1), b3 + hstep, voffB); PG8_STAGE(PG8_SA(1, 0), a3, voffA);
;             PG8_WAIT_V(8); PG8_WAIT_L(0); PG8_BAR; PG8_MMA(1, 0, At, B0); PG8_MMA(1, 1, At, B1); PG8_BAR; PG8_SCHED;
.Lp7s_m5:
	s_setprio 0
	s_barrier
	s_add_i32 s36, s61, s40
	v_lshl_add_u64 v[142:143], v[142:143], 0, s[6:7]
	s_mov_b32 m0, s36
	ds_read_b128 v[182:185], v149 offset:49152
	ds_read_b128 v[186:189], v149 offset:50176
	ds_read_b128 v[190:193], v149 offset:51200
	ds_read_b128 v[194:197], v149 offset:52224
	ds_read_b128 v[198:201], v149 offset:53248
	ds_read_b128 v[202:205], v149 offset:54272
	ds_read_b128 v[206:209], v149 offset:55296
	ds_read_b128 v[210:213], v149 offset:56320
	global_load_lds_dwordx4 v[142:143], off
	s_add_i32 m0, s36, 0x2000
	s_add_u32 s34, s34, 0x100080
	v_lshl_add_u64 v[142:143], v[214:215], 0, s[6:7]
	s_addc_u32 s35, s35, 0
	s_add_i32 s36, s62, s40
	global_load_lds_dwordx4 v[142:143], off
	v_lshl_add_u64 v[142:143], s[34:35], 0, v[132:133]
	s_mov_b32 m0, s36
	s_nop 0
	global_load_lds_dwordx4 v[142:143], off
	v_lshl_add_u64 v[142:143], s[34:35], 0, v[128:129]
	s_add_i32 m0, s36, 0x2000
	s_nop 0
	global_load_lds_dwordx4 v[142:143], off
	v_lshl_add_u64 v[142:143], v[216:217], 0, s[6:7]
	s_mov_b32 m0, s47
	s_nop 0
	global_load_lds_dwordx4 v[142:143], off
	v_lshl_add_u64 v[142:143], v[218:219], 0, s[6:7]
	s_mov_b32 m0, s48
	s_nop 0
	global_load_lds_dwordx4 v[142:143], off
	s_waitcnt vmcnt(8)
	s_waitcnt lgkmcnt(0)
	s_barrier
	s_setprio 1
	s_waitcnt lgkmcnt(0)
	s_bitcmp1_b32 s68, 2
	s_cbranch_scc0 .Lp7s_m6
	v_mfma_f32_16x16x32_bf16 v[60:63], v[150:153], v[182:185], v[60:63]
	v_mfma_f32_16x16x32_bf16 v[56:59], v[158:161], v[182:185], v[56:59]
	v_mfma_f32_16x16x32_bf16 v[48:51], v[150:153], v[190:193], v[48:51]
	v_mfma_f32_16x16x32_bf16 v[40:43], v[158:161], v[190:193], v[40:43]
	v_mfma_f32_16x16x32_bf16 v[32:35], v[150:153], v[198:201], v[32:35]
	v_mfma_f32_16x16x32_bf16 v[24:27], v[158:161], v[198:201], v[24:27]
	v_mfma_f32_16x16x32_bf16 v[16:19], v[150:153], v[206:209], v[16:19]
	v_mfma_f32_16x16x32_bf16 v[8:11], v[158:161], v[206:209], v[8:11]
	v_mfma_f32_16x16x32_bf16 v[60:63], v[154:157], v[186:189], v[60:63]
	v_mfma_f32_16x16x32_bf16 v[56:59], v[162:165], v[186:189], v[56:59]
	v_mfma_f32_16x16x32_bf16 v[48:51], v[154:157], v[194:197], v[48:51]
	v_mfma_f32_16x16x32_bf16 v[40:43], v[162:165], v[194:197], v[40:43]
	v_mfma_f32_16x16x32_bf16 v[32:35], v[154:157], v[202:205], v[32:35]
	v_mfma_f32_16x16x32_bf16 v[24:27], v[162:165], v[202:205], v[24:27]
	v_mfma_f32_16x16x32_bf16 v[16:19], v[154:157], v[210:213], v[16:19]
	v_mfma_f32_16x16x32_bf16 v[8:11], v[162:165], v[210:213], v[8:11]

; __device__ __forceinline__ unsigned cvt_pk_bf16(float lo, float hi) { unsigned r; asm volatile("v_cvt_pk_bf16_f32 %0, %1, %2" : "=v"(r) : "v"(lo), "v"(hi)); return r; }
;     __device__ __forceinline__ void operator()(const f32x4 (&acc)[2][2][4][2], const Unit& u, int wr, int wc, int fr, int fq) const {
;         const int row0 = u.pm * BM + wr * 64 + fr; int colt = u.pn * BM; bf16_t* base = O;
;         float sc = 1.f; if (split_cols) { const int t = colt / split_cols; base += (size_t)t * split_stride; colt -= t * split_cols; if (t == 0) sc = scale0; }
;         const int col0 = colt + wc * 32 + 8 * fq, bcol0 = u.pn * BM + wc * 32 + 8 * fq;
;         f32x4 bv[2][2];
; #pragma unroll
;         for (int bj = 0; bj < 2; ++bj)
; #pragma unroll
;             for (int n = 0; n < 2; ++n) bv[bj][n] = bias ? *(const f32x4*)(bias + bcol0 + bj * HALF + 4 * n) : (f32x4){0.f, 0.f, 0.f, 0.f};
; #pragma unroll
;         for (int ai = 0; ai < 2; ++ai)
; #pragma unroll
;             for (int m = 0; m < 4; ++m) { bf16_t* rowp = base + (size_t)(row0 + ai * HALF + m * 16) * ldc + col0;
; #pragma unroll
;                 for (int bj = 0; bj < 2; ++bj) { if (!((u.mask >> (2 * ai + bj)) & 1)) continue; f32x4 v0 = acc[ai][bj][m][0] + bv[bj][0], v1 = acc[ai][bj][m][1] + bv[bj][1];
;                     if (ACT == 1) { f32x2 a = gelu_pk((f32x2){v0[0], v0[1]}), b = gelu_pk((f32x2){v0[2], v0[3]}), c = gelu_pk((f32x2){v1[0], v1[1]}), d = gelu_pk((f32x2){v1[2], v1[3]});
;                         v0 = (f32x4){a.x, a.y, b.x, b.y}; v1 = (f32x4){c.x, c.y, d.x, d.y}; }
;                     v0 = v0 * sc; v1 = v1 * sc; u32x4 w; w.x = cvt_pk_bf16(v0[0], v0[1]); w.y = cvt_pk_bf16(v0[2], v0[3]); w.z = cvt_pk_bf16(v1[0], v1[1]); w.w = cvt_pk_bf16(v1[2], v1[3]);
;                     *(u32x4*)(rowp + bj * HALF) = w; } }
.Lp7s_m7:
	s_setprio 0
	s_barrier
	s_add_i32 s60, s60, 2
	s_add_u32 s30, s30, 0x100
	s_addc_u32 s31, s31, 0
	s_add_u32 s58, s58, 0x100
	s_addc_u32 s59, s59, 0
	s_cmp_gt_u32 s60, 61
	s_cbranch_scc0 .LBB0_1551
	s_and_b64 vcc, exec, s[8:9]
	s_cbranch_vccz .LBB0_1554
	s_barrier
.LBB0_1554:
	v_lshl_or_b32 v142, s55, 8, v146
	v_lshl_add_u32 v150, s28, 8, v144
	v_ashrrev_i32_e32 v143, 31, v142
	v_ashrrev_i32_e32 v151, 31, v150
	v_lshl_add_u64 v[152:153], v[142:143], 1, s[4:5]
	v_lshlrev_b64 v[142:143], 12, v[150:151]
	v_lshl_add_u64 v[142:143], v[152:153], 0, v[142:143]
	v_pk_add_f32 v[126:127], v[126:127], 0 op_sel_hi:[1,0]
	v_pk_add_f32 v[124:125], v[124:125], 0 op_sel_hi:[1,0]
	v_pk_add_f32 v[154:155], v[122:123], 0 op_sel_hi:[1,0]
	v_pk_add_f32 v[122:123], v[120:121], 0 op_sel_hi:[1,0]
	v_cvt_pk_bf16_f32 v120, v124, v125
	v_cvt_pk_bf16_f32 v121, v126, v127
	v_pk_add_f32 v[116:117], v[116:117], 0 op_sel_hi:[1,0]
	v_cvt_pk_bf16_f32 v122, v122, v123
	v_cvt_pk_bf16_f32 v123, v154, v155
	s_bitcmp1_b32 s68, 0
	s_cbranch_scc0 .Lp7s_s0
	global_store_dwordx4 v[142:143], v[120:123], off
.Lp7s_s0:
	v_pk_add_f32 v[118:119], v[118:119], 0 op_sel_hi:[1,0]
	v_pk_add_f32 v[112:113], v[112:113], 0 op_sel_hi:[1,0]
	v_pk_add_f32 v[120:121], v[110:111], 0 op_sel_hi:[1,0]
	v_pk_add_f32 v[110:111], v[108:109], 0 op_sel_hi:[1,0]
	v_cvt_pk_bf16_f32 v108, v116, v117
	v_cvt_pk_bf16_f32 v109, v118, v119
	v_pk_add_f32 v[100:101], v[100:101], 0 op_sel_hi:[1,0]
	v_cvt_pk_bf16_f32 v110, v110, v111
	v_cvt_pk_bf16_f32 v111, v120, v121
	s_bitcmp1_b32 s68, 1
	s_cbranch_scc0 .Lp7s_s1
	global_store_dwordx4 v[142:143], v[108:111], off offset:256
.Lp7s_s1:
	v_pk_add_f32 v[102:103], v[102:103], 0 op_sel_hi:[1,0]
	v_pk_add_f32 v[96:97], v[96:97], 0 op_sel_hi:[1,0]
	v_or_b32_e32 v108, 16, v150
	v_ashrrev_i32_e32 v109, 31, v108
	v_lshlrev_b64 v[108:109], 12, v[108:109]
	v_lshl_add_u64 v[108:109], v[152:153], 0, v[108:109]
	v_pk_add_f32 v[110:111], v[114:115], 0 op_sel_hi:[1,0]
	v_pk_add_f32 v[114:115], v[106:107], 0 op_sel_hi:[1,0]
	v_pk_add_f32 v[106:107], v[104:105], 0 op_sel_hi:[1,0]
	v_cvt_pk_bf16_f32 v104, v112, v113
	v_cvt_pk_bf16_f32 v105, v110, v111
	v_pk_add_f32 v[84:85], v[84:85], 0 op_sel_hi:[1,0]
	v_cvt_pk_bf16_f32 v106, v106, v107
	v_cvt_pk_bf16_f32 v107, v114, v115
	s_bitcmp1_b32 s68, 0
	s_cbranch_scc0 .Lp7s_s2
	global_store_dwordx4 v[108:109], v[104:107], off
.Lp7s_s2:
	v_pk_add_f32 v[86:87], v[86:87], 0 op_sel_hi:[1,0]
	v_pk_add_f32 v[80:81], v[80:81], 0 op_sel_hi:[1,0]
	v_pk_add_f32 v[104:105], v[94:95], 0 op_sel_hi:[1,0]
	v_pk_add_f32 v[94:95], v[92:93], 0 op_sel_hi:[1,0]
	v_cvt_pk_bf16_f32 v92, v100, v101
	v_cvt_pk_bf16_f32 v93, v102, v103
	v_pk_add_f32 v[70:71], v[70:71], 0 op_sel_hi:[1,0]
	v_cvt_pk_bf16_f32 v94, v94, v95
	v_cvt_pk_bf16_f32 v95, v104, v105
	s_bitcmp1_b32 s68, 1
	s_cbranch_scc0 .Lp7s_s3
	global_store_dwordx4 v[108:109], v[92:95], off offset:256
.Lp7s_s3:
	v_pk_add_f32 v[68:69], v[68:69], 0 op_sel_hi:[1,0]
	v_pk_add_f32 v[60:61], v[60:61], 0 op_sel_hi:[1,0]
	v_or_b32_e32 v92, 32, v150
	v_ashrrev_i32_e32 v93, 31, v92
	v_lshlrev_b64 v[92:93], 12, v[92:93]
	v_lshl_add_u64 v[92:93], v[152:153], 0, v[92:93]
	v_pk_add_f32 v[94:95], v[98:99], 0 op_sel_hi:[1,0]
	v_pk_add_f32 v[98:99], v[90:91], 0 op_sel_hi:[1,0]
	v_pk_add_f32 v[90:91], v[88:89], 0 op_sel_hi:[1,0]
	v_cvt_pk_bf16_f32 v88, v96, v97
	v_cvt_pk_bf16_f32 v89, v94, v95
	v_pk_add_f32 v[62:63], v[62:63], 0 op_sel_hi:[1,0]
	v_cvt_pk_bf16_f32 v90, v90, v91
	v_cvt_pk_bf16_f32 v91, v98, v99
	s_bitcmp1_b32 s68, 0
	s_cbranch_scc0 .Lp7s_s4
	global_store_dwordx4 v[92:93], v[88:91], off
.Lp7s_s4:
	v_pk_add_f32 v[54:55], v[54:55], 0 op_sel_hi:[1,0]
	v_pk_add_f32 v[52:53], v[52:53], 0 op_sel_hi:[1,0]
	v_pk_add_f32 v[88:89], v[78:79], 0 op_sel_hi:[1,0]
	v_pk_add_f32 v[78:79], v[76:77], 0 op_sel_hi:[1,0]
	v_cvt_pk_bf16_f32 v76, v84, v85
	v_cvt_pk_bf16_f32 v77, v86, v87
	v_pk_add_f32 v[48:49], v[48:49], 0 op_sel_hi:[1,0]
	v_cvt_pk_bf16_f32 v78, v78, v79
	v_cvt_pk_bf16_f32 v79, v88, v89
	s_bitcmp1_b32 s68, 1
	s_cbranch_scc0 .Lp7s_s5
	global_store_dwordx4 v[92:93], v[76:79], off offset:256
.Lp7s_s5:
	v_pk_add_f32 v[38:39], v[38:39], 0 op_sel_hi:[1,0]
	v_pk_add_f32 v[36:37], v[36:37], 0 op_sel_hi:[1,0]
	v_or_b32_e32 v76, 48, v150
	v_ashrrev_i32_e32 v77, 31, v76
	v_lshlrev_b64 v[76:77], 12, v[76:77]
	v_lshl_add_u64 v[76:77], v[152:153], 0, v[76:77]
	v_pk_add_f32 v[78:79], v[82:83], 0 op_sel_hi:[1,0]
	v_pk_add_f32 v[82:83], v[74:75], 0 op_sel_hi:[1,0]
	v_pk_add_f32 v[74:75], v[72:73], 0 op_sel_hi:[1,0]
	v_cvt_pk_bf16_f32 v72, v80, v81
	v_cvt_pk_bf16_f32 v73, v78, v79
	v_pk_add_f32 v[32:33], v[32:33], 0 op_sel_hi:[1,0]
	v_cvt_pk_bf16_f32 v74, v74, v75
	v_cvt_pk_bf16_f32 v75, v82, v83
	s_bitcmp1_b32 s68, 0
	s_cbranch_scc0 .Lp7s_s6
	global_store_dwordx4 v[76:77], v[72:75], off
; __device__ __forceinline__ unsigned cvt_pk_bf16(float lo, float hi) { unsigned r; asm volatile("v_cvt_pk_bf16_f32 %0, %1, %2" : "=v"(r) : "v"(lo), "v"(hi)); return r; }
;     __device__ __forceinline__ void operator()(const f32x4 (&acc)[2][2][4][2], const Unit& u, int wr, int wc, int fr, int fq) const {
;     ...
;             for (int m = 0; m < 4; ++m) { bf16_t* rowp = base + (size_t)(row0 + ai * HALF + m * 16) * ldc + col0;
; #pragma unroll
;                 for (int bj = 0; bj < 2; ++bj) { if (!((u.mask >> (2 * ai + bj)) & 1)) continue; f32x4 v0 = acc[ai][bj][m][0] + bv[bj][0], v1 = acc[ai][bj][m][1] + bv[bj][1];
;                     if (ACT == 1) { f32x2 a = gelu_pk((f32x2){v0[0], v0[1]}), b = gelu_pk((f32x2){v0[2], v0[3]}), c = gelu_pk((f32x2){v1[0], v1[1]}), d = gelu_pk((f32x2){v1[2], v1[3]});
;                         v0 = (f32x4){a.x, a.y, b.x, b.y}; v1 = (f32x4){c.x, c.y, d.x, d.y}; }
;                     v0 = v0 * sc; v1 = v1 * sc; u32x4 w; w.x = cvt_pk_bf16(v0[0], v0[1]); w.y = cvt_pk_bf16(v0[2], v0[3]); w.z = cvt_pk_bf16(v1[0], v1[1]); w.w = cvt_pk_bf16(v1[2], v1[3]);
;                     *(u32x4*)(rowp + bj * HALF) = w; } }
.Lp7s_s6:
	v_pk_add_f32 v[22:23], v[22:23], 0 op_sel_hi:[1,0]
	v_pk_add_f32 v[20:21], v[20:21], 0 op_sel_hi:[1,0]
	v_pk_add_f32 v[72:73], v[66:67], 0 op_sel_hi:[1,0]
	v_pk_add_f32 v[66:67], v[64:65], 0 op_sel_hi:[1,0]
	v_cvt_pk_bf16_f32 v64, v68, v69
	v_cvt_pk_bf16_f32 v65, v70, v71
	v_pk_add_f32 v[16:17], v[16:17], 0 op_sel_hi:[1,0]
	v_cvt_pk_bf16_f32 v66, v66, v67
	v_cvt_pk_bf16_f32 v67, v72, v73
	s_bitcmp1_b32 s68, 1
	s_cbranch_scc0 .Lp7s_s7
	global_store_dwordx4 v[76:77], v[64:67], off offset:256
.Lp7s_s7:
	v_pk_add_f32 v[6:7], v[6:7], 0 op_sel_hi:[1,0]
	v_pk_add_f32 v[4:5], v[4:5], 0 op_sel_hi:[1,0]
	v_pk_add_f32 v[66:67], v[58:59], 0 op_sel_hi:[1,0]
	v_pk_add_f32 v[58:59], v[56:57], 0 op_sel_hi:[1,0]
	v_cvt_pk_bf16_f32 v56, v60, v61
	v_add_co_u32_e32 v60, vcc, s51, v142
	v_cvt_pk_bf16_f32 v57, v62, v63
	v_cvt_pk_bf16_f32 v58, v58, v59
	v_cvt_pk_bf16_f32 v59, v66, v67
	v_lshl_add_u64 v[64:65], v[142:143], 0, s[10:11]
	s_nop 0
	v_addc_co_u32_e32 v61, vcc, 0, v143, vcc
	s_bitcmp1_b32 s68, 2
	s_cbranch_scc0 .Lp7s_s8
	global_store_dwordx4 v[60:61], v[56:59], off
.Lp7s_s8:
	s_nop 1
	v_pk_add_f32 v[56:57], v[46:47], 0 op_sel_hi:[1,0]
	v_pk_add_f32 v[46:47], v[44:45], 0 op_sel_hi:[1,0]
	v_cvt_pk_bf16_f32 v44, v52, v53
	v_cvt_pk_bf16_f32 v45, v54, v55
	s_nop 0
	v_cvt_pk_bf16_f32 v46, v46, v47
	v_cvt_pk_bf16_f32 v47, v56, v57
	s_bitcmp1_b32 s68, 3
	s_cbranch_scc0 .Lp7s_s9
	global_store_dwordx4 v[64:65], v[44:47], off offset:256
.Lp7s_s9:
	s_nop 1
	v_pk_add_f32 v[46:47], v[50:51], 0 op_sel_hi:[1,0]
	v_pk_add_f32 v[50:51], v[42:43], 0 op_sel_hi:[1,0]
	v_pk_add_f32 v[42:43], v[40:41], 0 op_sel_hi:[1,0]
	v_cvt_pk_bf16_f32 v40, v48, v49
	v_cvt_pk_bf16_f32 v41, v46, v47
	v_add_co_u32_e32 v46, vcc, s52, v142
	v_cvt_pk_bf16_f32 v42, v42, v43
	v_cvt_pk_bf16_f32 v43, v50, v51
	v_lshl_add_u64 v[44:45], v[142:143], 0, s[12:13]
	s_nop 0
	v_addc_co_u32_e32 v47, vcc, 0, v143, vcc
	s_bitcmp1_b32 s68, 2
	s_cbranch_scc0 .Lp7s_s10
	global_store_dwordx4 v[46:47], v[40:43], off
.Lp7s_s10:
	s_nop 1
	v_pk_add_f32 v[40:41], v[30:31], 0 op_sel_hi:[1,0]
	v_pk_add_f32 v[30:31], v[28:29], 0 op_sel_hi:[1,0]
	v_cvt_pk_bf16_f32 v28, v36, v37
	v_cvt_pk_bf16_f32 v29, v38, v39
	s_nop 0
	v_cvt_pk_bf16_f32 v30, v30, v31
	v_cvt_pk_bf16_f32 v31, v40, v41
	s_bitcmp1_b32 s68, 3
	s_cbranch_scc0 .Lp7s_s11
	global_store_dwordx4 v[44:45], v[28:31], off offset:256
.Lp7s_s11:
	s_nop 1
	v_pk_add_f32 v[30:31], v[34:35], 0 op_sel_hi:[1,0]
	v_pk_add_f32 v[34:35], v[26:27], 0 op_sel_hi:[1,0]
	v_pk_add_f32 v[26:27], v[24:25], 0 op_sel_hi:[1,0]
	v_cvt_pk_bf16_f32 v24, v32, v33
	v_cvt_pk_bf16_f32 v25, v30, v31
	v_add_co_u32_e32 v30, vcc, s53, v142
	v_cvt_pk_bf16_f32 v26, v26, v27
	v_cvt_pk_bf16_f32 v27, v34, v35
	v_lshl_add_u64 v[28:29], v[142:143], 0, s[14:15]
	s_nop 0
	v_addc_co_u32_e32 v31, vcc, 0, v143, vcc
	s_bitcmp1_b32 s68, 2
	s_cbranch_scc0 .Lp7s_s12
	global_store_dwordx4 v[30:31], v[24:27], off
.Lp7s_s12:
	s_nop 1
	v_pk_add_f32 v[24:25], v[14:15], 0 op_sel_hi:[1,0]
	v_pk_add_f32 v[14:15], v[12:13], 0 op_sel_hi:[1,0]
	v_cvt_pk_bf16_f32 v12, v20, v21
	v_cvt_pk_bf16_f32 v13, v22, v23
	s_nop 0
	v_cvt_pk_bf16_f32 v14, v14, v15
	v_cvt_pk_bf16_f32 v15, v24, v25
	s_bitcmp1_b32 s68, 3
	s_cbranch_scc0 .Lp7s_s13
	global_store_dwordx4 v[28:29], v[12:15], off offset:256
.Lp7s_s13:
	s_nop 1
	v_pk_add_f32 v[14:15], v[18:19], 0 op_sel_hi:[1,0]
	v_pk_add_f32 v[18:19], v[10:11], 0 op_sel_hi:[1,0]
	v_pk_add_f32 v[10:11], v[8:9], 0 op_sel_hi:[1,0]
	v_cvt_pk_bf16_f32 v8, v16, v17
	v_cvt_pk_bf16_f32 v9, v14, v15
	v_add_co_u32_e32 v14, vcc, s54, v142
	v_lshl_add_u64 v[12:13], v[142:143], 0, s[16:17]
	s_nop 0
	v_addc_co_u32_e32 v15, vcc, 0, v143, vcc
	v_cvt_pk_bf16_f32 v10, v10, v11
	v_cvt_pk_bf16_f32 v11, v18, v19
	s_bitcmp1_b32 s68, 2
	s_cbranch_scc0 .Lp7s_s14
	global_store_dwordx4 v[14:15], v[8:11], off
.Lp7s_s14:
	s_andn2_b64 vcc, exec, s[22:23]
	s_mov_b64 s[22:23], -1
	v_pk_add_f32 v[8:9], v[2:3], 0 op_sel_hi:[1,0]
	v_pk_add_f32 v[2:3], v[0:1], 0 op_sel_hi:[1,0]
	v_cvt_pk_bf16_f32 v0, v4, v5
	v_cvt_pk_bf16_f32 v1, v6, v7
	s_nop 0
	v_cvt_pk_bf16_f32 v2, v2, v3
	v_cvt_pk_bf16_f32 v3, v8, v9
	s_bitcmp1_b32 s68, 3
	s_cbranch_scc0 .Lp7s_s15
	global_store_dwordx4 v[12:13], v[0:3], off offset:256
.Lp7s_s15:
	s_cbranch_vccnz .LBB0_1546
	s_andn2_b64 vcc, exec, s[0:1]
	s_cbranch_vccnz .LBB0_1545
	s_barrier
	s_branch .LBB0_1545
